# v19 with the in-loop accumulator zeroing done by 32 v_pk_mov_b32 per segment instead of 64 v_mov_b32
# speedup vs baseline: 1.0021x; 1.0021x over previous
.LBB0_158:
	ds_read_b128 v[146:149], v160
	ds_read_b128 v[150:153], v160 offset:1024
	ds_read_b128 v[164:167], v160 offset:2048
	ds_read_b128 v[168:171], v160 offset:3072
	ds_read_b128 v[172:175], v161
	ds_read_b128 v[176:179], v161 offset:1024
	ds_read_b128 v[180:183], v161 offset:2048
	ds_read_b128 v[184:187], v161 offset:3072
	s_add_u32 s50, s48, 0xfffc0080
	s_addc_u32 s51, s49, -1
	s_cmp_eq_u32 s78, 12
	s_cselect_b32 s53, s35, s51
	s_cselect_b32 s52, s74, s50
	s_cselect_b32 s51, s31, s77
	s_cselect_b32 s50, s75, s76
	v_lshl_add_u64 v[154:155], s[48:49], 0, v[138:139]
	s_add_i32 m0, s6, 0xc000
	ds_read_b128 v[188:191], v162
	ds_read_b128 v[192:195], v162 offset:1024
	ds_read_b128 v[196:199], v162 offset:2048
	ds_read_b128 v[200:203], v162 offset:3072
	ds_read_b128 v[204:207], v162 offset:4096
	ds_read_b128 v[208:211], v162 offset:5120
	ds_read_b128 v[212:215], v162 offset:6144
	ds_read_b128 v[218:221], v162 offset:7168
	global_load_lds_dwordx4 v[154:155], off
	v_lshl_add_u64 v[154:155], s[48:49], 0, v[140:141]
	s_add_i32 m0, s6, 0xe000
	s_nop 0
	global_load_lds_dwordx4 v[154:155], off
	s_cmp_lg_u32 s78, -2
	s_cbranch_scc1 .Lzacc0a
	v_pk_mov_b32 v[64:65], 0, 0
	v_pk_mov_b32 v[66:67], 0, 0
	v_pk_mov_b32 v[68:69], 0, 0
	v_pk_mov_b32 v[70:71], 0, 0
	v_pk_mov_b32 v[72:73], 0, 0
	v_pk_mov_b32 v[74:75], 0, 0
	v_pk_mov_b32 v[76:77], 0, 0
	v_pk_mov_b32 v[78:79], 0, 0
	v_pk_mov_b32 v[80:81], 0, 0
	v_pk_mov_b32 v[82:83], 0, 0
	v_pk_mov_b32 v[84:85], 0, 0
	v_pk_mov_b32 v[86:87], 0, 0
	v_pk_mov_b32 v[88:89], 0, 0
	v_pk_mov_b32 v[90:91], 0, 0
	v_pk_mov_b32 v[92:93], 0, 0
	v_pk_mov_b32 v[94:95], 0, 0
	v_pk_mov_b32 v[96:97], 0, 0
	v_pk_mov_b32 v[98:99], 0, 0
	v_pk_mov_b32 v[100:101], 0, 0
	v_pk_mov_b32 v[102:103], 0, 0
	v_pk_mov_b32 v[104:105], 0, 0
	v_pk_mov_b32 v[106:107], 0, 0
	v_pk_mov_b32 v[108:109], 0, 0
	v_pk_mov_b32 v[110:111], 0, 0
	v_pk_mov_b32 v[112:113], 0, 0
	v_pk_mov_b32 v[114:115], 0, 0
	v_pk_mov_b32 v[116:117], 0, 0
	v_pk_mov_b32 v[118:119], 0, 0
	v_pk_mov_b32 v[120:121], 0, 0
	v_pk_mov_b32 v[122:123], 0, 0
	v_pk_mov_b32 v[124:125], 0, 0
	v_pk_mov_b32 v[126:127], 0, 0
.Lzacc0a:
	s_waitcnt vmcnt(8)
	s_waitcnt lgkmcnt(0)
	s_barrier
	s_setprio 1
	s_waitcnt lgkmcnt(0)
	v_mfma_f32_16x16x32_bf16 v[124:127], v[146:149], v[188:191], v[124:127]
	v_mfma_f32_16x16x32_bf16 v[120:123], v[164:167], v[188:191], v[120:123]
	v_mfma_f32_16x16x32_bf16 v[116:119], v[146:149], v[196:199], v[116:119]
	v_mfma_f32_16x16x32_bf16 v[112:115], v[164:167], v[196:199], v[112:115]
	v_mfma_f32_16x16x32_bf16 v[100:103], v[146:149], v[204:207], v[100:103]
	v_mfma_f32_16x16x32_bf16 v[96:99], v[164:167], v[204:207], v[96:99]
	v_mfma_f32_16x16x32_bf16 v[84:87], v[146:149], v[212:215], v[84:87]
	v_mfma_f32_16x16x32_bf16 v[80:83], v[164:167], v[212:215], v[80:83]
	v_mfma_f32_16x16x32_bf16 v[124:127], v[150:153], v[192:195], v[124:127]
	v_mfma_f32_16x16x32_bf16 v[120:123], v[168:171], v[192:195], v[120:123]
	v_mfma_f32_16x16x32_bf16 v[116:119], v[150:153], v[200:203], v[116:119]
	v_mfma_f32_16x16x32_bf16 v[112:115], v[168:171], v[200:203], v[112:115]
	v_mfma_f32_16x16x32_bf16 v[100:103], v[150:153], v[208:211], v[100:103]
	v_mfma_f32_16x16x32_bf16 v[96:99], v[168:171], v[208:211], v[96:99]
	v_mfma_f32_16x16x32_bf16 v[84:87], v[150:153], v[218:221], v[84:87]
	v_mfma_f32_16x16x32_bf16 v[80:83], v[168:171], v[218:221], v[80:83]
	s_setprio 0
	s_setprio 1
	v_mfma_f32_16x16x32_bf16 v[108:111], v[172:175], v[188:191], v[108:111]
	v_mfma_f32_16x16x32_bf16 v[104:107], v[180:183], v[188:191], v[104:107]
	v_mfma_f32_16x16x32_bf16 v[92:95], v[172:175], v[196:199], v[92:95]
	v_mfma_f32_16x16x32_bf16 v[88:91], v[180:183], v[196:199], v[88:91]
	v_mfma_f32_16x16x32_bf16 v[76:79], v[172:175], v[204:207], v[76:79]
	v_mfma_f32_16x16x32_bf16 v[72:75], v[180:183], v[204:207], v[72:75]
	v_mfma_f32_16x16x32_bf16 v[68:71], v[172:175], v[212:215], v[68:71]
	v_mfma_f32_16x16x32_bf16 v[64:67], v[180:183], v[212:215], v[64:67]
	v_mfma_f32_16x16x32_bf16 v[108:111], v[176:179], v[192:195], v[108:111]
	v_mfma_f32_16x16x32_bf16 v[104:107], v[184:187], v[192:195], v[104:107]
	v_mfma_f32_16x16x32_bf16 v[92:95], v[176:179], v[200:203], v[92:95]
	v_mfma_f32_16x16x32_bf16 v[88:91], v[184:187], v[200:203], v[88:91]
	v_mfma_f32_16x16x32_bf16 v[76:79], v[176:179], v[208:211], v[76:79]
	v_mfma_f32_16x16x32_bf16 v[72:75], v[184:187], v[208:211], v[72:75]
	v_mfma_f32_16x16x32_bf16 v[68:71], v[176:179], v[218:221], v[68:71]
	v_mfma_f32_16x16x32_bf16 v[64:67], v[184:187], v[218:221], v[64:67]
	s_setprio 0
	s_barrier
	s_add_i32 s79, s64, s58
	v_lshl_add_u64 v[154:155], s[50:51], 0, v[132:133]
	s_mov_b32 m0, s79
	ds_read_b128 v[188:191], v162 offset:16384
	ds_read_b128 v[192:195], v162 offset:17408
	ds_read_b128 v[196:199], v162 offset:18432
	ds_read_b128 v[200:203], v162 offset:19456
	ds_read_b128 v[204:207], v162 offset:20480
	ds_read_b128 v[208:211], v162 offset:21504
	ds_read_b128 v[212:215], v162 offset:22528
	ds_read_b128 v[218:221], v162 offset:23552
	global_load_lds_dwordx4 v[154:155], off
	s_add_i32 m0, s79, 0x2000
	s_add_u32 s80, s50, 0x40000
	v_lshl_add_u64 v[222:223], s[50:51], 0, v[128:129]
	s_addc_u32 s81, s51, 0
	s_add_i32 s79, s65, s58
	global_load_lds_dwordx4 v[222:223], off
	v_lshl_add_u64 v[224:225], s[80:81], 0, v[132:133]
	s_mov_b32 m0, s79
	v_lshl_add_u64 v[226:227], s[52:53], 0, v[130:131]
	global_load_lds_dwordx4 v[224:225], off
	v_lshl_add_u64 v[224:225], s[80:81], 0, v[128:129]
	s_add_i32 m0, s79, 0x2000
	s_nop 0
	global_load_lds_dwordx4 v[224:225], off
	v_lshl_add_u64 v[224:225], s[52:53], 0, v[134:135]
	s_mov_b32 m0, s6
	s_nop 0
	global_load_lds_dwordx4 v[224:225], off
	s_mov_b32 m0, s21
	s_nop 0
	global_load_lds_dwordx4 v[226:227], off
	s_cmp_lg_u32 s78, -2
	s_cbranch_scc1 .Lzacc0b
	v_pk_mov_b32 v[0:1], 0, 0
	v_pk_mov_b32 v[2:3], 0, 0
	v_pk_mov_b32 v[4:5], 0, 0
	v_pk_mov_b32 v[6:7], 0, 0
	v_pk_mov_b32 v[8:9], 0, 0
	v_pk_mov_b32 v[10:11], 0, 0
	v_pk_mov_b32 v[12:13], 0, 0
	v_pk_mov_b32 v[14:15], 0, 0
	v_pk_mov_b32 v[16:17], 0, 0
	v_pk_mov_b32 v[18:19], 0, 0
	v_pk_mov_b32 v[20:21], 0, 0
	v_pk_mov_b32 v[22:23], 0, 0
	v_pk_mov_b32 v[24:25], 0, 0
	v_pk_mov_b32 v[26:27], 0, 0
	v_pk_mov_b32 v[28:29], 0, 0
	v_pk_mov_b32 v[30:31], 0, 0
	v_pk_mov_b32 v[32:33], 0, 0
	v_pk_mov_b32 v[34:35], 0, 0
	v_pk_mov_b32 v[36:37], 0, 0
	v_pk_mov_b32 v[38:39], 0, 0
	v_pk_mov_b32 v[40:41], 0, 0
	v_pk_mov_b32 v[42:43], 0, 0
	v_pk_mov_b32 v[44:45], 0, 0
	v_pk_mov_b32 v[46:47], 0, 0
	v_pk_mov_b32 v[48:49], 0, 0
	v_pk_mov_b32 v[50:51], 0, 0
	v_pk_mov_b32 v[52:53], 0, 0
	v_pk_mov_b32 v[54:55], 0, 0
	v_pk_mov_b32 v[56:57], 0, 0
	v_pk_mov_b32 v[58:59], 0, 0
	v_pk_mov_b32 v[60:61], 0, 0
	v_pk_mov_b32 v[62:63], 0, 0

.LBB0_294:
	ds_read_b128 v[128:131], v209
	ds_read_b128 v[132:135], v209 offset:1024
	ds_read_b128 v[136:139], v209 offset:2048
	ds_read_b128 v[140:143], v209 offset:3072
	ds_read_b128 v[144:147], v210
	ds_read_b128 v[148:151], v210 offset:1024
	ds_read_b128 v[152:155], v210 offset:2048
	ds_read_b128 v[156:159], v210 offset:3072
	s_add_u32 s54, s52, 0xfffc0080
	s_addc_u32 s55, s53, -1
	s_cmp_eq_u32 s76, 12
	s_cselect_b32 s57, s5, s55
	s_cselect_b32 s56, s17, s54
	s_cselect_b32 s55, s31, s75
	s_cselect_b32 s54, s35, s51
	v_lshl_add_u64 v[214:215], s[52:53], 0, v[184:185]
	s_add_i32 m0, s62, 0xc000
	ds_read_b128 v[160:163], v211
	ds_read_b128 v[164:167], v211 offset:1024
	ds_read_b128 v[168:171], v211 offset:2048
	ds_read_b128 v[172:175], v211 offset:3072
	ds_read_b128 v[192:195], v211 offset:4096
	ds_read_b128 v[196:199], v211 offset:5120
	ds_read_b128 v[200:203], v211 offset:6144
	ds_read_b128 v[218:221], v211 offset:7168
	global_load_lds_dwordx4 v[214:215], off
	v_lshl_add_u64 v[214:215], s[52:53], 0, v[186:187]
	s_add_i32 m0, s62, 0xe000
	s_nop 0
	global_load_lds_dwordx4 v[214:215], off
	s_cmp_lg_u32 s76, -2
	s_cbranch_scc1 .Lzacc1a
	v_pk_mov_b32 v[64:65], 0, 0
	v_pk_mov_b32 v[66:67], 0, 0
	v_pk_mov_b32 v[68:69], 0, 0
	v_pk_mov_b32 v[70:71], 0, 0
	v_pk_mov_b32 v[72:73], 0, 0
	v_pk_mov_b32 v[74:75], 0, 0
	v_pk_mov_b32 v[76:77], 0, 0
	v_pk_mov_b32 v[78:79], 0, 0
	v_pk_mov_b32 v[80:81], 0, 0
	v_pk_mov_b32 v[82:83], 0, 0
	v_pk_mov_b32 v[84:85], 0, 0
	v_pk_mov_b32 v[86:87], 0, 0
	v_pk_mov_b32 v[88:89], 0, 0
	v_pk_mov_b32 v[90:91], 0, 0
	v_pk_mov_b32 v[92:93], 0, 0
	v_pk_mov_b32 v[94:95], 0, 0
	v_pk_mov_b32 v[96:97], 0, 0
	v_pk_mov_b32 v[98:99], 0, 0
	v_pk_mov_b32 v[100:101], 0, 0
	v_pk_mov_b32 v[102:103], 0, 0
	v_pk_mov_b32 v[104:105], 0, 0
	v_pk_mov_b32 v[106:107], 0, 0
	v_pk_mov_b32 v[108:109], 0, 0
	v_pk_mov_b32 v[110:111], 0, 0
	v_pk_mov_b32 v[112:113], 0, 0
	v_pk_mov_b32 v[114:115], 0, 0
	v_pk_mov_b32 v[116:117], 0, 0
	v_pk_mov_b32 v[118:119], 0, 0
	v_pk_mov_b32 v[120:121], 0, 0
	v_pk_mov_b32 v[122:123], 0, 0
	v_pk_mov_b32 v[124:125], 0, 0
	v_pk_mov_b32 v[126:127], 0, 0
.Lzacc1a:
	s_waitcnt vmcnt(8)
	s_waitcnt lgkmcnt(0)
	s_barrier
	s_setprio 1
	s_waitcnt lgkmcnt(0)
	v_mfma_f32_16x16x32_bf16 v[124:127], v[128:131], v[160:163], v[124:127]
	v_mfma_f32_16x16x32_bf16 v[120:123], v[136:139], v[160:163], v[120:123]
	v_mfma_f32_16x16x32_bf16 v[108:111], v[128:131], v[168:171], v[108:111]
	v_mfma_f32_16x16x32_bf16 v[104:107], v[136:139], v[168:171], v[104:107]
	v_mfma_f32_16x16x32_bf16 v[92:95], v[128:131], v[192:195], v[92:95]
	v_mfma_f32_16x16x32_bf16 v[88:91], v[136:139], v[192:195], v[88:91]
	v_mfma_f32_16x16x32_bf16 v[76:79], v[128:131], v[200:203], v[76:79]
	v_mfma_f32_16x16x32_bf16 v[72:75], v[136:139], v[200:203], v[72:75]
	v_mfma_f32_16x16x32_bf16 v[124:127], v[132:135], v[164:167], v[124:127]
	v_mfma_f32_16x16x32_bf16 v[120:123], v[140:143], v[164:167], v[120:123]
	v_mfma_f32_16x16x32_bf16 v[108:111], v[132:135], v[172:175], v[108:111]
	v_mfma_f32_16x16x32_bf16 v[104:107], v[140:143], v[172:175], v[104:107]
	v_mfma_f32_16x16x32_bf16 v[92:95], v[132:135], v[196:199], v[92:95]
	v_mfma_f32_16x16x32_bf16 v[88:91], v[140:143], v[196:199], v[88:91]
	v_mfma_f32_16x16x32_bf16 v[76:79], v[132:135], v[218:221], v[76:79]
	v_mfma_f32_16x16x32_bf16 v[72:75], v[140:143], v[218:221], v[72:75]
	s_setprio 0
	s_setprio 1
	v_mfma_f32_16x16x32_bf16 v[116:119], v[144:147], v[160:163], v[116:119]
	v_mfma_f32_16x16x32_bf16 v[112:115], v[152:155], v[160:163], v[112:115]
	v_mfma_f32_16x16x32_bf16 v[100:103], v[144:147], v[168:171], v[100:103]
	v_mfma_f32_16x16x32_bf16 v[96:99], v[152:155], v[168:171], v[96:99]
	v_mfma_f32_16x16x32_bf16 v[84:87], v[144:147], v[192:195], v[84:87]
	v_mfma_f32_16x16x32_bf16 v[80:83], v[152:155], v[192:195], v[80:83]
	v_mfma_f32_16x16x32_bf16 v[68:71], v[144:147], v[200:203], v[68:71]
	v_mfma_f32_16x16x32_bf16 v[64:67], v[152:155], v[200:203], v[64:67]
	v_mfma_f32_16x16x32_bf16 v[116:119], v[148:151], v[164:167], v[116:119]
	v_mfma_f32_16x16x32_bf16 v[112:115], v[156:159], v[164:167], v[112:115]
	v_mfma_f32_16x16x32_bf16 v[100:103], v[148:151], v[172:175], v[100:103]
	v_mfma_f32_16x16x32_bf16 v[96:99], v[156:159], v[172:175], v[96:99]
	v_mfma_f32_16x16x32_bf16 v[84:87], v[148:151], v[196:199], v[84:87]
	v_mfma_f32_16x16x32_bf16 v[80:83], v[156:159], v[196:199], v[80:83]
	v_mfma_f32_16x16x32_bf16 v[68:71], v[148:151], v[218:221], v[68:71]
	v_mfma_f32_16x16x32_bf16 v[64:67], v[156:159], v[218:221], v[64:67]
	s_setprio 0
	s_barrier
	s_add_i32 s77, s72, s61
	v_lshl_add_u64 v[214:215], s[54:55], 0, v[178:179]
	s_mov_b32 m0, s77
	ds_read_b128 v[160:163], v211 offset:16384
	ds_read_b128 v[164:167], v211 offset:17408
	ds_read_b128 v[168:171], v211 offset:18432
	ds_read_b128 v[172:175], v211 offset:19456
	ds_read_b128 v[192:195], v211 offset:20480
	ds_read_b128 v[196:199], v211 offset:21504
	ds_read_b128 v[200:203], v211 offset:22528
	ds_read_b128 v[218:221], v211 offset:23552
	global_load_lds_dwordx4 v[214:215], off
	s_add_i32 m0, s77, 0x2000
	s_add_u32 s78, s54, 0x40000
	v_lshl_add_u64 v[222:223], s[54:55], 0, v[182:183]
	s_addc_u32 s79, s55, 0
	s_add_i32 s77, s73, s61
	global_load_lds_dwordx4 v[222:223], off
	v_lshl_add_u64 v[224:225], s[78:79], 0, v[178:179]
	s_mov_b32 m0, s77
	v_lshl_add_u64 v[226:227], s[56:57], 0, v[180:181]
	global_load_lds_dwordx4 v[224:225], off
	v_lshl_add_u64 v[224:225], s[78:79], 0, v[182:183]
	s_add_i32 m0, s77, 0x2000
	s_nop 0
	global_load_lds_dwordx4 v[224:225], off
	v_lshl_add_u64 v[224:225], s[56:57], 0, v[176:177]
	s_mov_b32 m0, s62
	s_nop 0
	global_load_lds_dwordx4 v[224:225], off
	s_mov_b32 m0, s63
	s_nop 0
	global_load_lds_dwordx4 v[226:227], off
	s_cmp_lg_u32 s76, -2
	s_cbranch_scc1 .Lzacc1b
	v_pk_mov_b32 v[0:1], 0, 0
	v_pk_mov_b32 v[2:3], 0, 0
	v_pk_mov_b32 v[4:5], 0, 0
	v_pk_mov_b32 v[6:7], 0, 0
	v_pk_mov_b32 v[8:9], 0, 0
	v_pk_mov_b32 v[10:11], 0, 0
	v_pk_mov_b32 v[12:13], 0, 0
	v_pk_mov_b32 v[14:15], 0, 0
	v_pk_mov_b32 v[16:17], 0, 0
	v_pk_mov_b32 v[18:19], 0, 0
	v_pk_mov_b32 v[20:21], 0, 0
	v_pk_mov_b32 v[22:23], 0, 0
	v_pk_mov_b32 v[24:25], 0, 0
	v_pk_mov_b32 v[26:27], 0, 0
	v_pk_mov_b32 v[28:29], 0, 0
	v_pk_mov_b32 v[30:31], 0, 0
	v_pk_mov_b32 v[32:33], 0, 0
	v_pk_mov_b32 v[34:35], 0, 0
	v_pk_mov_b32 v[36:37], 0, 0
	v_pk_mov_b32 v[38:39], 0, 0
	v_pk_mov_b32 v[40:41], 0, 0
	v_pk_mov_b32 v[42:43], 0, 0
	v_pk_mov_b32 v[44:45], 0, 0
	v_pk_mov_b32 v[46:47], 0, 0
	v_pk_mov_b32 v[48:49], 0, 0
	v_pk_mov_b32 v[50:51], 0, 0
	v_pk_mov_b32 v[52:53], 0, 0
	v_pk_mov_b32 v[54:55], 0, 0
	v_pk_mov_b32 v[56:57], 0, 0
	v_pk_mov_b32 v[58:59], 0, 0
	v_pk_mov_b32 v[60:61], 0, 0
	v_pk_mov_b32 v[62:63], 0, 0

.LBB0_381:
	ds_read_b128 v[128:131], v204
	ds_read_b128 v[132:135], v204 offset:1024
	ds_read_b128 v[136:139], v204 offset:2048
	ds_read_b128 v[140:143], v204 offset:3072
	ds_read_b128 v[144:147], v205
	ds_read_b128 v[148:151], v205 offset:1024
	ds_read_b128 v[152:155], v205 offset:2048
	ds_read_b128 v[156:159], v205 offset:3072
	s_add_u32 s12, s10, 0xfffc0080
	s_addc_u32 s13, s11, -1
	s_cmp_eq_u32 s84, 12
	s_cselect_b32 s15, s5, s13
	s_cselect_b32 s14, s51, s12
	s_cselect_b32 s13, s54, s59
	s_cselect_b32 s12, s55, s57
	v_lshl_add_u64 v[214:215], s[10:11], 0, v[178:179]
	s_add_i32 m0, s53, 0xc000
	ds_read_b128 v[160:163], v206
	ds_read_b128 v[164:167], v206 offset:1024
	ds_read_b128 v[186:189], v206 offset:2048
	ds_read_b128 v[190:193], v206 offset:3072
	ds_read_b128 v[194:197], v206 offset:4096
	ds_read_b128 v[198:201], v206 offset:5120
	ds_read_b128 v[210:213], v206 offset:6144
	ds_read_b128 v[218:221], v206 offset:7168
	global_load_lds_dwordx4 v[214:215], off
	v_lshl_add_u64 v[214:215], s[10:11], 0, v[180:181]
	s_add_i32 m0, s53, 0xe000
	s_nop 0
	global_load_lds_dwordx4 v[214:215], off
	s_cmp_lg_u32 s84, -2
	s_cbranch_scc1 .Lzacc2a
	v_pk_mov_b32 v[24:25], 0, 0
	v_pk_mov_b32 v[26:27], 0, 0
	v_pk_mov_b32 v[36:37], 0, 0
	v_pk_mov_b32 v[38:39], 0, 0
	v_pk_mov_b32 v[52:53], 0, 0
	v_pk_mov_b32 v[54:55], 0, 0
	v_pk_mov_b32 v[64:65], 0, 0
	v_pk_mov_b32 v[66:67], 0, 0
	v_pk_mov_b32 v[80:81], 0, 0
	v_pk_mov_b32 v[82:83], 0, 0
	v_pk_mov_b32 v[84:85], 0, 0
	v_pk_mov_b32 v[86:87], 0, 0
	v_pk_mov_b32 v[88:89], 0, 0
	v_pk_mov_b32 v[90:91], 0, 0
	v_pk_mov_b32 v[92:93], 0, 0
	v_pk_mov_b32 v[94:95], 0, 0
	v_pk_mov_b32 v[96:97], 0, 0
	v_pk_mov_b32 v[98:99], 0, 0
	v_pk_mov_b32 v[100:101], 0, 0
	v_pk_mov_b32 v[102:103], 0, 0
	v_pk_mov_b32 v[104:105], 0, 0
	v_pk_mov_b32 v[106:107], 0, 0
	v_pk_mov_b32 v[108:109], 0, 0
	v_pk_mov_b32 v[110:111], 0, 0
	v_pk_mov_b32 v[112:113], 0, 0
	v_pk_mov_b32 v[114:115], 0, 0
	v_pk_mov_b32 v[116:117], 0, 0
	v_pk_mov_b32 v[118:119], 0, 0
	v_pk_mov_b32 v[120:121], 0, 0
	v_pk_mov_b32 v[122:123], 0, 0
	v_pk_mov_b32 v[124:125], 0, 0
	v_pk_mov_b32 v[126:127], 0, 0
.Lzacc2a:
	s_waitcnt vmcnt(8)
	s_waitcnt lgkmcnt(0)
	s_barrier
	s_setprio 1
	s_waitcnt lgkmcnt(0)
	v_mfma_f32_16x16x32_bf16 v[124:127], v[128:131], v[160:163], v[124:127]
	v_mfma_f32_16x16x32_bf16 v[120:123], v[136:139], v[160:163], v[120:123]
	v_mfma_f32_16x16x32_bf16 v[116:119], v[128:131], v[186:189], v[116:119]
	v_mfma_f32_16x16x32_bf16 v[112:115], v[136:139], v[186:189], v[112:115]
	v_mfma_f32_16x16x32_bf16 v[108:111], v[128:131], v[194:197], v[108:111]
	v_mfma_f32_16x16x32_bf16 v[104:107], v[136:139], v[194:197], v[104:107]
	v_mfma_f32_16x16x32_bf16 v[92:95], v[128:131], v[210:213], v[92:95]
	v_mfma_f32_16x16x32_bf16 v[84:87], v[136:139], v[210:213], v[84:87]
	v_mfma_f32_16x16x32_bf16 v[124:127], v[132:135], v[164:167], v[124:127]
	v_mfma_f32_16x16x32_bf16 v[120:123], v[140:143], v[164:167], v[120:123]
	v_mfma_f32_16x16x32_bf16 v[116:119], v[132:135], v[190:193], v[116:119]
	v_mfma_f32_16x16x32_bf16 v[112:115], v[140:143], v[190:193], v[112:115]
	v_mfma_f32_16x16x32_bf16 v[108:111], v[132:135], v[198:201], v[108:111]
	v_mfma_f32_16x16x32_bf16 v[104:107], v[140:143], v[198:201], v[104:107]
	v_mfma_f32_16x16x32_bf16 v[92:95], v[132:135], v[218:221], v[92:95]
	v_mfma_f32_16x16x32_bf16 v[84:87], v[140:143], v[218:221], v[84:87]
	s_setprio 0
	s_setprio 1
	v_mfma_f32_16x16x32_bf16 v[88:91], v[144:147], v[160:163], v[88:91]
	v_mfma_f32_16x16x32_bf16 v[24:27], v[152:155], v[160:163], v[24:27]
	v_mfma_f32_16x16x32_bf16 v[100:103], v[144:147], v[186:189], v[100:103]
	v_mfma_f32_16x16x32_bf16 v[36:39], v[152:155], v[186:189], v[36:39]
	v_mfma_f32_16x16x32_bf16 v[96:99], v[144:147], v[194:197], v[96:99]
	v_mfma_f32_16x16x32_bf16 v[52:55], v[152:155], v[194:197], v[52:55]
	v_mfma_f32_16x16x32_bf16 v[80:83], v[144:147], v[210:213], v[80:83]
	v_mfma_f32_16x16x32_bf16 v[64:67], v[152:155], v[210:213], v[64:67]
	v_mfma_f32_16x16x32_bf16 v[88:91], v[148:151], v[164:167], v[88:91]
	v_mfma_f32_16x16x32_bf16 v[24:27], v[156:159], v[164:167], v[24:27]
	v_mfma_f32_16x16x32_bf16 v[100:103], v[148:151], v[190:193], v[100:103]
	v_mfma_f32_16x16x32_bf16 v[36:39], v[156:159], v[190:193], v[36:39]
	v_mfma_f32_16x16x32_bf16 v[96:99], v[148:151], v[198:201], v[96:99]
	v_mfma_f32_16x16x32_bf16 v[52:55], v[156:159], v[198:201], v[52:55]
	v_mfma_f32_16x16x32_bf16 v[80:83], v[148:151], v[218:221], v[80:83]
	v_mfma_f32_16x16x32_bf16 v[64:67], v[156:159], v[218:221], v[64:67]
	s_setprio 0
	s_barrier
	s_add_i32 s85, s83, s67
	v_lshl_add_u64 v[214:215], s[12:13], 0, v[172:173]
	s_mov_b32 m0, s85
	ds_read_b128 v[160:163], v206 offset:16384
	ds_read_b128 v[164:167], v206 offset:17408
	ds_read_b128 v[186:189], v206 offset:18432
	ds_read_b128 v[190:193], v206 offset:19456
	ds_read_b128 v[194:197], v206 offset:20480
	ds_read_b128 v[198:201], v206 offset:21504
	ds_read_b128 v[210:213], v206 offset:22528
	ds_read_b128 v[218:221], v206 offset:23552
	global_load_lds_dwordx4 v[214:215], off
	s_add_i32 m0, s85, 0x2000
	s_add_u32 s92, s12, 0x40000
	v_lshl_add_u64 v[222:223], s[12:13], 0, v[168:169]
	s_addc_u32 s93, s13, 0
	s_add_i32 s85, s94, s67
	global_load_lds_dwordx4 v[222:223], off
	v_lshl_add_u64 v[224:225], s[92:93], 0, v[172:173]
	s_mov_b32 m0, s85
	v_lshl_add_u64 v[226:227], s[14:15], 0, v[170:171]
	global_load_lds_dwordx4 v[224:225], off
	v_lshl_add_u64 v[224:225], s[92:93], 0, v[168:169]
	s_add_i32 m0, s85, 0x2000
	s_nop 0
	global_load_lds_dwordx4 v[224:225], off
	v_lshl_add_u64 v[224:225], s[14:15], 0, v[174:175]
	s_mov_b32 m0, s53
	s_nop 0
	global_load_lds_dwordx4 v[224:225], off
	s_mov_b32 m0, s68
	s_nop 0
	global_load_lds_dwordx4 v[226:227], off
	s_cmp_lg_u32 s84, -2
	s_cbranch_scc1 .Lzacc2b
	v_pk_mov_b32 v[0:1], 0, 0
	v_pk_mov_b32 v[2:3], 0, 0
	v_pk_mov_b32 v[4:5], 0, 0
	v_pk_mov_b32 v[6:7], 0, 0
	v_pk_mov_b32 v[8:9], 0, 0
	v_pk_mov_b32 v[10:11], 0, 0
	v_pk_mov_b32 v[12:13], 0, 0
	v_pk_mov_b32 v[14:15], 0, 0
	v_pk_mov_b32 v[16:17], 0, 0
	v_pk_mov_b32 v[18:19], 0, 0
	v_pk_mov_b32 v[20:21], 0, 0
	v_pk_mov_b32 v[22:23], 0, 0
	v_pk_mov_b32 v[28:29], 0, 0
	v_pk_mov_b32 v[30:31], 0, 0
	v_pk_mov_b32 v[32:33], 0, 0
	v_pk_mov_b32 v[34:35], 0, 0
	v_pk_mov_b32 v[40:41], 0, 0
	v_pk_mov_b32 v[42:43], 0, 0
	v_pk_mov_b32 v[44:45], 0, 0
	v_pk_mov_b32 v[46:47], 0, 0
	v_pk_mov_b32 v[48:49], 0, 0
	v_pk_mov_b32 v[50:51], 0, 0
	v_pk_mov_b32 v[56:57], 0, 0
	v_pk_mov_b32 v[58:59], 0, 0
	v_pk_mov_b32 v[60:61], 0, 0
	v_pk_mov_b32 v[62:63], 0, 0
	v_pk_mov_b32 v[68:69], 0, 0
	v_pk_mov_b32 v[70:71], 0, 0
	v_pk_mov_b32 v[72:73], 0, 0
	v_pk_mov_b32 v[74:75], 0, 0
	v_pk_mov_b32 v[76:77], 0, 0
	v_pk_mov_b32 v[78:79], 0, 0

.LBB0_541:
	ds_read_b128 v[112:115], v223
	ds_read_b128 v[124:127], v223 offset:1024
	ds_read_b128 v[136:139], v223 offset:2048
	ds_read_b128 v[140:143], v223 offset:3072
	ds_read_b128 v[144:147], v224
	ds_read_b128 v[148:151], v224 offset:1024
	ds_read_b128 v[152:155], v224 offset:2048
	ds_read_b128 v[156:159], v224 offset:3072
	s_add_u32 s60, s58, 0x100
	s_addc_u32 s61, s59, 0
	s_cmp_eq_u32 s55, 40
	s_cselect_b32 s65, s13, s61
	s_cselect_b32 s64, s12, s60
	s_cselect_b32 s63, s57, s54
	s_cselect_b32 s62, s56, s15
	v_lshl_add_u64 v[208:209], s[58:59], 0, v[192:193]
	s_add_i32 m0, s69, 0xc000
	ds_read_b128 v[160:163], v225
	ds_read_b128 v[164:167], v225 offset:1024
	ds_read_b128 v[168:171], v225 offset:2048
	ds_read_b128 v[172:175], v225 offset:3072
	ds_read_b128 v[176:179], v225 offset:4096
	ds_read_b128 v[180:183], v225 offset:5120
	ds_read_b128 v[200:203], v225 offset:6144
	ds_read_b128 v[204:207], v225 offset:7168
	global_load_lds_dwordx4 v[208:209], off
	v_lshl_add_u64 v[208:209], s[58:59], 0, v[194:195]
	s_add_i32 m0, s69, 0xe000
	s_nop 0
	global_load_lds_dwordx4 v[208:209], off
	s_cmp_lg_u32 s55, -2
	s_cbranch_scc1 .Lzacc3a
	v_pk_mov_b32 v[64:65], 0, 0
	v_pk_mov_b32 v[66:67], 0, 0
	v_pk_mov_b32 v[68:69], 0, 0
	v_pk_mov_b32 v[70:71], 0, 0
	v_pk_mov_b32 v[72:73], 0, 0
	v_pk_mov_b32 v[74:75], 0, 0
	v_pk_mov_b32 v[76:77], 0, 0
	v_pk_mov_b32 v[78:79], 0, 0
	v_pk_mov_b32 v[80:81], 0, 0
	v_pk_mov_b32 v[82:83], 0, 0
	v_pk_mov_b32 v[84:85], 0, 0
	v_pk_mov_b32 v[86:87], 0, 0
	v_pk_mov_b32 v[88:89], 0, 0
	v_pk_mov_b32 v[90:91], 0, 0
	v_pk_mov_b32 v[92:93], 0, 0
	v_pk_mov_b32 v[94:95], 0, 0
	v_pk_mov_b32 v[96:97], 0, 0
	v_pk_mov_b32 v[98:99], 0, 0
	v_pk_mov_b32 v[100:101], 0, 0
	v_pk_mov_b32 v[102:103], 0, 0
	v_pk_mov_b32 v[104:105], 0, 0
	v_pk_mov_b32 v[106:107], 0, 0
	v_pk_mov_b32 v[108:109], 0, 0
	v_pk_mov_b32 v[110:111], 0, 0
	v_pk_mov_b32 v[116:117], 0, 0
	v_pk_mov_b32 v[118:119], 0, 0
	v_pk_mov_b32 v[120:121], 0, 0
	v_pk_mov_b32 v[122:123], 0, 0
	v_pk_mov_b32 v[128:129], 0, 0
	v_pk_mov_b32 v[130:131], 0, 0
	v_pk_mov_b32 v[132:133], 0, 0
	v_pk_mov_b32 v[134:135], 0, 0
.Lzacc3a:
	s_waitcnt vmcnt(8)
	s_waitcnt lgkmcnt(0)
	s_barrier
	s_setprio 1
	s_waitcnt lgkmcnt(0)
	v_mfma_f32_16x16x32_bf16 v[132:135], v[112:115], v[160:163], v[132:135]
	v_mfma_f32_16x16x32_bf16 v[128:131], v[136:139], v[160:163], v[128:131]
	v_mfma_f32_16x16x32_bf16 v[108:111], v[112:115], v[168:171], v[108:111]
	v_mfma_f32_16x16x32_bf16 v[104:107], v[136:139], v[168:171], v[104:107]
	v_mfma_f32_16x16x32_bf16 v[92:95], v[112:115], v[176:179], v[92:95]
	v_mfma_f32_16x16x32_bf16 v[88:91], v[136:139], v[176:179], v[88:91]
	v_mfma_f32_16x16x32_bf16 v[76:79], v[112:115], v[200:203], v[76:79]
	v_mfma_f32_16x16x32_bf16 v[72:75], v[136:139], v[200:203], v[72:75]
	v_mfma_f32_16x16x32_bf16 v[132:135], v[124:127], v[164:167], v[132:135]
	v_mfma_f32_16x16x32_bf16 v[128:131], v[140:143], v[164:167], v[128:131]
	v_mfma_f32_16x16x32_bf16 v[108:111], v[124:127], v[172:175], v[108:111]
	v_mfma_f32_16x16x32_bf16 v[104:107], v[140:143], v[172:175], v[104:107]
	v_mfma_f32_16x16x32_bf16 v[92:95], v[124:127], v[180:183], v[92:95]
	v_mfma_f32_16x16x32_bf16 v[88:91], v[140:143], v[180:183], v[88:91]
	v_mfma_f32_16x16x32_bf16 v[76:79], v[124:127], v[204:207], v[76:79]
	v_mfma_f32_16x16x32_bf16 v[72:75], v[140:143], v[204:207], v[72:75]
	s_setprio 0
	s_setprio 1
	v_mfma_f32_16x16x32_bf16 v[120:123], v[144:147], v[160:163], v[120:123]
	v_mfma_f32_16x16x32_bf16 v[116:119], v[152:155], v[160:163], v[116:119]
	v_mfma_f32_16x16x32_bf16 v[100:103], v[144:147], v[168:171], v[100:103]
	v_mfma_f32_16x16x32_bf16 v[96:99], v[152:155], v[168:171], v[96:99]
	v_mfma_f32_16x16x32_bf16 v[84:87], v[144:147], v[176:179], v[84:87]
	v_mfma_f32_16x16x32_bf16 v[80:83], v[152:155], v[176:179], v[80:83]
	v_mfma_f32_16x16x32_bf16 v[68:71], v[144:147], v[200:203], v[68:71]
	v_mfma_f32_16x16x32_bf16 v[64:67], v[152:155], v[200:203], v[64:67]
	v_mfma_f32_16x16x32_bf16 v[120:123], v[148:151], v[164:167], v[120:123]
	v_mfma_f32_16x16x32_bf16 v[116:119], v[156:159], v[164:167], v[116:119]
	v_mfma_f32_16x16x32_bf16 v[100:103], v[148:151], v[172:175], v[100:103]
	v_mfma_f32_16x16x32_bf16 v[96:99], v[156:159], v[172:175], v[96:99]
	v_mfma_f32_16x16x32_bf16 v[84:87], v[148:151], v[180:183], v[84:87]
	v_mfma_f32_16x16x32_bf16 v[80:83], v[156:159], v[180:183], v[80:83]
	v_mfma_f32_16x16x32_bf16 v[68:71], v[148:151], v[204:207], v[68:71]
	v_mfma_f32_16x16x32_bf16 v[64:67], v[156:159], v[204:207], v[64:67]
	s_setprio 0
	s_barrier
	s_add_i32 s58, s78, s68
	v_lshl_add_u64 v[208:209], s[62:63], 0, v[186:187]
	s_mov_b32 m0, s58
	ds_read_b128 v[160:163], v225 offset:16384
	ds_read_b128 v[164:167], v225 offset:17408
	ds_read_b128 v[168:171], v225 offset:18432
	ds_read_b128 v[172:175], v225 offset:19456
	ds_read_b128 v[176:179], v225 offset:20480
	ds_read_b128 v[180:183], v225 offset:21504
	ds_read_b128 v[200:203], v225 offset:22528
	ds_read_b128 v[204:207], v225 offset:23552
	global_load_lds_dwordx4 v[208:209], off
	s_add_i32 m0, s58, 0x2000
	s_add_u32 s58, s62, 0xb0000
	v_lshl_add_u64 v[210:211], s[62:63], 0, v[190:191]
	s_addc_u32 s59, s63, 0
	s_add_i32 s83, s79, s68
	global_load_lds_dwordx4 v[210:211], off
	v_lshl_add_u64 v[212:213], s[58:59], 0, v[186:187]
	s_mov_b32 m0, s83
	v_lshl_add_u64 v[214:215], s[64:65], 0, v[188:189]
	global_load_lds_dwordx4 v[212:213], off
	v_lshl_add_u64 v[212:213], s[58:59], 0, v[190:191]
	s_add_i32 m0, s83, 0x2000
	s_nop 0
	global_load_lds_dwordx4 v[212:213], off
	v_lshl_add_u64 v[212:213], s[64:65], 0, v[184:185]
	s_mov_b32 m0, s69
	s_nop 0
	global_load_lds_dwordx4 v[212:213], off
	s_mov_b32 m0, s72
	s_nop 0
	global_load_lds_dwordx4 v[214:215], off
	s_cmp_lg_u32 s55, -2
	s_cbranch_scc1 .Lzacc3b
	v_pk_mov_b32 v[0:1], 0, 0
	v_pk_mov_b32 v[2:3], 0, 0
	v_pk_mov_b32 v[4:5], 0, 0
	v_pk_mov_b32 v[6:7], 0, 0
	v_pk_mov_b32 v[8:9], 0, 0
	v_pk_mov_b32 v[10:11], 0, 0
	v_pk_mov_b32 v[12:13], 0, 0
	v_pk_mov_b32 v[14:15], 0, 0
	v_pk_mov_b32 v[16:17], 0, 0
	v_pk_mov_b32 v[18:19], 0, 0
	v_pk_mov_b32 v[20:21], 0, 0
	v_pk_mov_b32 v[22:23], 0, 0
	v_pk_mov_b32 v[24:25], 0, 0
	v_pk_mov_b32 v[26:27], 0, 0
	v_pk_mov_b32 v[28:29], 0, 0
	v_pk_mov_b32 v[30:31], 0, 0
	v_pk_mov_b32 v[32:33], 0, 0
	v_pk_mov_b32 v[34:35], 0, 0
	v_pk_mov_b32 v[36:37], 0, 0
	v_pk_mov_b32 v[38:39], 0, 0
	v_pk_mov_b32 v[40:41], 0, 0
	v_pk_mov_b32 v[42:43], 0, 0
	v_pk_mov_b32 v[44:45], 0, 0
	v_pk_mov_b32 v[46:47], 0, 0
	v_pk_mov_b32 v[48:49], 0, 0
	v_pk_mov_b32 v[50:51], 0, 0
	v_pk_mov_b32 v[52:53], 0, 0
	v_pk_mov_b32 v[54:55], 0, 0
	v_pk_mov_b32 v[56:57], 0, 0
	v_pk_mov_b32 v[58:59], 0, 0
	v_pk_mov_b32 v[60:61], 0, 0
	v_pk_mov_b32 v[62:63], 0, 0

.LBB0_628:
	ds_read_b128 v[160:163], v154
	ds_read_b128 v[164:167], v154 offset:1024
	ds_read_b128 v[168:171], v154 offset:2048
	ds_read_b128 v[172:175], v154 offset:3072
	ds_read_b128 v[176:179], v155
	ds_read_b128 v[180:183], v155 offset:1024
	ds_read_b128 v[184:187], v155 offset:2048
	ds_read_b128 v[188:191], v155 offset:3072
	s_add_u32 s36, s34, 0xfffc0080
	s_addc_u32 s37, s35, -1
	s_cmp_eq_u32 s68, 12
	s_cselect_b32 s39, s21, s37
	s_cselect_b32 s38, s27, s36
	s_cselect_b32 s37, s25, s67
	s_cselect_b32 s36, s65, s66
	v_lshl_add_u64 v[152:153], s[34:35], 0, v[140:141]
	s_add_i32 m0, s8, 0xc000
	ds_read_b128 v[192:195], v156
	ds_read_b128 v[196:199], v156 offset:1024
	ds_read_b128 v[200:203], v156 offset:2048
	ds_read_b128 v[204:207], v156 offset:3072
	ds_read_b128 v[208:211], v156 offset:4096
	ds_read_b128 v[212:215], v156 offset:5120
	ds_read_b128 v[218:221], v156 offset:6144
	ds_read_b128 v[222:225], v156 offset:7168
	global_load_lds_dwordx4 v[152:153], off
	v_lshl_add_u64 v[152:153], s[34:35], 0, v[142:143]
	s_add_i32 m0, s8, 0xe000
	s_nop 0
	global_load_lds_dwordx4 v[152:153], off
	s_cmp_lg_u32 s68, -2
	s_cbranch_scc1 .Lzacc4a
	v_pk_mov_b32 v[64:65], 0, 0
	v_pk_mov_b32 v[66:67], 0, 0
	v_pk_mov_b32 v[68:69], 0, 0
	v_pk_mov_b32 v[70:71], 0, 0
	v_pk_mov_b32 v[72:73], 0, 0
	v_pk_mov_b32 v[74:75], 0, 0
	v_pk_mov_b32 v[76:77], 0, 0
	v_pk_mov_b32 v[78:79], 0, 0
	v_pk_mov_b32 v[80:81], 0, 0
	v_pk_mov_b32 v[82:83], 0, 0
	v_pk_mov_b32 v[84:85], 0, 0
	v_pk_mov_b32 v[86:87], 0, 0
	v_pk_mov_b32 v[88:89], 0, 0
	v_pk_mov_b32 v[90:91], 0, 0
	v_pk_mov_b32 v[92:93], 0, 0
	v_pk_mov_b32 v[94:95], 0, 0
	v_pk_mov_b32 v[96:97], 0, 0
	v_pk_mov_b32 v[98:99], 0, 0
	v_pk_mov_b32 v[100:101], 0, 0
	v_pk_mov_b32 v[102:103], 0, 0
	v_pk_mov_b32 v[104:105], 0, 0
	v_pk_mov_b32 v[106:107], 0, 0
	v_pk_mov_b32 v[108:109], 0, 0
	v_pk_mov_b32 v[110:111], 0, 0
	v_pk_mov_b32 v[112:113], 0, 0
	v_pk_mov_b32 v[114:115], 0, 0
	v_pk_mov_b32 v[116:117], 0, 0
	v_pk_mov_b32 v[118:119], 0, 0
	v_pk_mov_b32 v[120:121], 0, 0
	v_pk_mov_b32 v[122:123], 0, 0
	v_pk_mov_b32 v[124:125], 0, 0
	v_pk_mov_b32 v[126:127], 0, 0
.Lzacc4a:
	s_waitcnt vmcnt(8)
	s_waitcnt lgkmcnt(0)
	s_barrier
	s_setprio 1
	s_waitcnt lgkmcnt(0)
	v_mfma_f32_16x16x32_bf16 v[124:127], v[160:163], v[192:195], v[124:127]
	v_mfma_f32_16x16x32_bf16 v[120:123], v[168:171], v[192:195], v[120:123]
	v_mfma_f32_16x16x32_bf16 v[116:119], v[160:163], v[200:203], v[116:119]
	v_mfma_f32_16x16x32_bf16 v[108:111], v[168:171], v[200:203], v[108:111]
	v_mfma_f32_16x16x32_bf16 v[100:103], v[160:163], v[208:211], v[100:103]
	v_mfma_f32_16x16x32_bf16 v[92:95], v[168:171], v[208:211], v[92:95]
	v_mfma_f32_16x16x32_bf16 v[84:87], v[160:163], v[218:221], v[84:87]
	v_mfma_f32_16x16x32_bf16 v[76:79], v[168:171], v[218:221], v[76:79]
	v_mfma_f32_16x16x32_bf16 v[124:127], v[164:167], v[196:199], v[124:127]
	v_mfma_f32_16x16x32_bf16 v[120:123], v[172:175], v[196:199], v[120:123]
	v_mfma_f32_16x16x32_bf16 v[116:119], v[164:167], v[204:207], v[116:119]
	v_mfma_f32_16x16x32_bf16 v[108:111], v[172:175], v[204:207], v[108:111]
	v_mfma_f32_16x16x32_bf16 v[100:103], v[164:167], v[212:215], v[100:103]
	v_mfma_f32_16x16x32_bf16 v[92:95], v[172:175], v[212:215], v[92:95]
	v_mfma_f32_16x16x32_bf16 v[84:87], v[164:167], v[222:225], v[84:87]
	v_mfma_f32_16x16x32_bf16 v[76:79], v[172:175], v[222:225], v[76:79]
	s_setprio 0
	s_setprio 1
	v_mfma_f32_16x16x32_bf16 v[112:115], v[176:179], v[192:195], v[112:115]
	v_mfma_f32_16x16x32_bf16 v[104:107], v[184:187], v[192:195], v[104:107]
	v_mfma_f32_16x16x32_bf16 v[96:99], v[176:179], v[200:203], v[96:99]
	v_mfma_f32_16x16x32_bf16 v[88:91], v[184:187], v[200:203], v[88:91]
	v_mfma_f32_16x16x32_bf16 v[80:83], v[176:179], v[208:211], v[80:83]
	v_mfma_f32_16x16x32_bf16 v[72:75], v[184:187], v[208:211], v[72:75]
	v_mfma_f32_16x16x32_bf16 v[68:71], v[176:179], v[218:221], v[68:71]
	v_mfma_f32_16x16x32_bf16 v[64:67], v[184:187], v[218:221], v[64:67]
	v_mfma_f32_16x16x32_bf16 v[112:115], v[180:183], v[196:199], v[112:115]
	v_mfma_f32_16x16x32_bf16 v[104:107], v[188:191], v[196:199], v[104:107]
	v_mfma_f32_16x16x32_bf16 v[96:99], v[180:183], v[204:207], v[96:99]
	v_mfma_f32_16x16x32_bf16 v[88:91], v[188:191], v[204:207], v[88:91]
	v_mfma_f32_16x16x32_bf16 v[80:83], v[180:183], v[212:215], v[80:83]
	v_mfma_f32_16x16x32_bf16 v[72:75], v[188:191], v[212:215], v[72:75]
	v_mfma_f32_16x16x32_bf16 v[68:71], v[180:183], v[222:225], v[68:71]
	v_mfma_f32_16x16x32_bf16 v[64:67], v[188:191], v[222:225], v[64:67]
	s_setprio 0
	s_barrier
	s_add_i32 s69, s63, s54
	v_lshl_add_u64 v[152:153], s[36:37], 0, v[132:133]
	s_mov_b32 m0, s69
	ds_read_b128 v[192:195], v156 offset:16384
	ds_read_b128 v[196:199], v156 offset:17408
	ds_read_b128 v[200:203], v156 offset:18432
	ds_read_b128 v[204:207], v156 offset:19456
	ds_read_b128 v[208:211], v156 offset:20480
	ds_read_b128 v[212:215], v156 offset:21504
	ds_read_b128 v[218:221], v156 offset:22528
	ds_read_b128 v[222:225], v156 offset:23552
	global_load_lds_dwordx4 v[152:153], off
	s_add_i32 m0, s69, 0x2000
	s_add_u32 s72, s36, 0x40000
	v_lshl_add_u64 v[226:227], s[36:37], 0, v[128:129]
	s_addc_u32 s73, s37, 0
	s_add_i32 s69, s64, s54
	global_load_lds_dwordx4 v[226:227], off
	v_lshl_add_u64 v[228:229], s[72:73], 0, v[132:133]
	s_mov_b32 m0, s69
	v_lshl_add_u64 v[230:231], s[38:39], 0, v[130:131]
	global_load_lds_dwordx4 v[228:229], off
	v_lshl_add_u64 v[228:229], s[72:73], 0, v[128:129]
	s_add_i32 m0, s69, 0x2000
	s_nop 0
	global_load_lds_dwordx4 v[228:229], off
	v_lshl_add_u64 v[228:229], s[38:39], 0, v[134:135]
	s_mov_b32 m0, s8
	s_nop 0
	global_load_lds_dwordx4 v[228:229], off
	s_mov_b32 m0, s55
	s_nop 0
	global_load_lds_dwordx4 v[230:231], off
	s_cmp_lg_u32 s68, -2
	s_cbranch_scc1 .Lzacc4b
	v_pk_mov_b32 v[0:1], 0, 0
	v_pk_mov_b32 v[2:3], 0, 0
	v_pk_mov_b32 v[4:5], 0, 0
	v_pk_mov_b32 v[6:7], 0, 0
	v_pk_mov_b32 v[8:9], 0, 0
	v_pk_mov_b32 v[10:11], 0, 0
	v_pk_mov_b32 v[12:13], 0, 0
	v_pk_mov_b32 v[14:15], 0, 0
	v_pk_mov_b32 v[16:17], 0, 0
	v_pk_mov_b32 v[18:19], 0, 0
	v_pk_mov_b32 v[20:21], 0, 0
	v_pk_mov_b32 v[22:23], 0, 0
	v_pk_mov_b32 v[24:25], 0, 0
	v_pk_mov_b32 v[26:27], 0, 0
	v_pk_mov_b32 v[28:29], 0, 0
	v_pk_mov_b32 v[30:31], 0, 0
	v_pk_mov_b32 v[32:33], 0, 0
	v_pk_mov_b32 v[34:35], 0, 0
	v_pk_mov_b32 v[36:37], 0, 0
	v_pk_mov_b32 v[38:39], 0, 0
	v_pk_mov_b32 v[40:41], 0, 0
	v_pk_mov_b32 v[42:43], 0, 0
	v_pk_mov_b32 v[44:45], 0, 0
	v_pk_mov_b32 v[46:47], 0, 0
	v_pk_mov_b32 v[48:49], 0, 0
	v_pk_mov_b32 v[50:51], 0, 0
	v_pk_mov_b32 v[52:53], 0, 0
	v_pk_mov_b32 v[54:55], 0, 0
	v_pk_mov_b32 v[56:57], 0, 0
	v_pk_mov_b32 v[58:59], 0, 0
	v_pk_mov_b32 v[60:61], 0, 0
	v_pk_mov_b32 v[62:63], 0, 0

.LBB0_904:
	ds_read_b128 v[112:115], v223
	ds_read_b128 v[124:127], v223 offset:1024
	ds_read_b128 v[136:139], v223 offset:2048
	ds_read_b128 v[140:143], v223 offset:3072
	ds_read_b128 v[144:147], v224
	ds_read_b128 v[148:151], v224 offset:1024
	ds_read_b128 v[152:155], v224 offset:2048
	ds_read_b128 v[156:159], v224 offset:3072
	s_add_u32 s46, s60, 0xfffc0080
	s_addc_u32 s47, s61, -1
	s_cmp_eq_u32 s59, 12
	s_cselect_b32 s65, s5, s47
	s_cselect_b32 s64, s13, s46
	s_cselect_b32 s63, s35, s55
	s_cselect_b32 s62, s37, s54
	v_lshl_add_u64 v[208:209], s[60:61], 0, v[192:193]
	s_add_i32 m0, s70, 0xc000
	ds_read_b128 v[160:163], v225
	ds_read_b128 v[164:167], v225 offset:1024
	ds_read_b128 v[168:171], v225 offset:2048
	ds_read_b128 v[172:175], v225 offset:3072
	ds_read_b128 v[176:179], v225 offset:4096
	ds_read_b128 v[180:183], v225 offset:5120
	ds_read_b128 v[200:203], v225 offset:6144
	ds_read_b128 v[204:207], v225 offset:7168
	global_load_lds_dwordx4 v[208:209], off
	v_lshl_add_u64 v[208:209], s[60:61], 0, v[194:195]
	s_add_i32 m0, s70, 0xe000
	s_nop 0
	global_load_lds_dwordx4 v[208:209], off
	s_cmp_lg_u32 s59, -2
	s_cbranch_scc1 .Lzacc5a
	v_pk_mov_b32 v[64:65], 0, 0
	v_pk_mov_b32 v[66:67], 0, 0
	v_pk_mov_b32 v[68:69], 0, 0
	v_pk_mov_b32 v[70:71], 0, 0
	v_pk_mov_b32 v[72:73], 0, 0
	v_pk_mov_b32 v[74:75], 0, 0
	v_pk_mov_b32 v[76:77], 0, 0
	v_pk_mov_b32 v[78:79], 0, 0
	v_pk_mov_b32 v[80:81], 0, 0
	v_pk_mov_b32 v[82:83], 0, 0
	v_pk_mov_b32 v[84:85], 0, 0
	v_pk_mov_b32 v[86:87], 0, 0
	v_pk_mov_b32 v[88:89], 0, 0
	v_pk_mov_b32 v[90:91], 0, 0
	v_pk_mov_b32 v[92:93], 0, 0
	v_pk_mov_b32 v[94:95], 0, 0
	v_pk_mov_b32 v[96:97], 0, 0
	v_pk_mov_b32 v[98:99], 0, 0
	v_pk_mov_b32 v[100:101], 0, 0
	v_pk_mov_b32 v[102:103], 0, 0
	v_pk_mov_b32 v[104:105], 0, 0
	v_pk_mov_b32 v[106:107], 0, 0
	v_pk_mov_b32 v[108:109], 0, 0
	v_pk_mov_b32 v[110:111], 0, 0
	v_pk_mov_b32 v[116:117], 0, 0
	v_pk_mov_b32 v[118:119], 0, 0
	v_pk_mov_b32 v[120:121], 0, 0
	v_pk_mov_b32 v[122:123], 0, 0
	v_pk_mov_b32 v[128:129], 0, 0
	v_pk_mov_b32 v[130:131], 0, 0
	v_pk_mov_b32 v[132:133], 0, 0
	v_pk_mov_b32 v[134:135], 0, 0
.Lzacc5a:
	s_waitcnt vmcnt(8)
	s_waitcnt lgkmcnt(0)
	s_barrier
	s_setprio 1
	s_waitcnt lgkmcnt(0)
	v_mfma_f32_16x16x32_bf16 v[132:135], v[112:115], v[160:163], v[132:135]
	v_mfma_f32_16x16x32_bf16 v[128:131], v[136:139], v[160:163], v[128:131]
	v_mfma_f32_16x16x32_bf16 v[108:111], v[112:115], v[168:171], v[108:111]
	v_mfma_f32_16x16x32_bf16 v[104:107], v[136:139], v[168:171], v[104:107]
	v_mfma_f32_16x16x32_bf16 v[92:95], v[112:115], v[176:179], v[92:95]
	v_mfma_f32_16x16x32_bf16 v[88:91], v[136:139], v[176:179], v[88:91]
	v_mfma_f32_16x16x32_bf16 v[76:79], v[112:115], v[200:203], v[76:79]
	v_mfma_f32_16x16x32_bf16 v[72:75], v[136:139], v[200:203], v[72:75]
	v_mfma_f32_16x16x32_bf16 v[132:135], v[124:127], v[164:167], v[132:135]
	v_mfma_f32_16x16x32_bf16 v[128:131], v[140:143], v[164:167], v[128:131]
	v_mfma_f32_16x16x32_bf16 v[108:111], v[124:127], v[172:175], v[108:111]
	v_mfma_f32_16x16x32_bf16 v[104:107], v[140:143], v[172:175], v[104:107]
	v_mfma_f32_16x16x32_bf16 v[92:95], v[124:127], v[180:183], v[92:95]
	v_mfma_f32_16x16x32_bf16 v[88:91], v[140:143], v[180:183], v[88:91]
	v_mfma_f32_16x16x32_bf16 v[76:79], v[124:127], v[204:207], v[76:79]
	v_mfma_f32_16x16x32_bf16 v[72:75], v[140:143], v[204:207], v[72:75]
	s_setprio 0
	s_setprio 1
	v_mfma_f32_16x16x32_bf16 v[120:123], v[144:147], v[160:163], v[120:123]
	v_mfma_f32_16x16x32_bf16 v[116:119], v[152:155], v[160:163], v[116:119]
	v_mfma_f32_16x16x32_bf16 v[100:103], v[144:147], v[168:171], v[100:103]
	v_mfma_f32_16x16x32_bf16 v[96:99], v[152:155], v[168:171], v[96:99]
	v_mfma_f32_16x16x32_bf16 v[84:87], v[144:147], v[176:179], v[84:87]
	v_mfma_f32_16x16x32_bf16 v[80:83], v[152:155], v[176:179], v[80:83]
	v_mfma_f32_16x16x32_bf16 v[68:71], v[144:147], v[200:203], v[68:71]
	v_mfma_f32_16x16x32_bf16 v[64:67], v[152:155], v[200:203], v[64:67]
	v_mfma_f32_16x16x32_bf16 v[120:123], v[148:151], v[164:167], v[120:123]
	v_mfma_f32_16x16x32_bf16 v[116:119], v[156:159], v[164:167], v[116:119]
	v_mfma_f32_16x16x32_bf16 v[100:103], v[148:151], v[172:175], v[100:103]
	v_mfma_f32_16x16x32_bf16 v[96:99], v[156:159], v[172:175], v[96:99]
	v_mfma_f32_16x16x32_bf16 v[84:87], v[148:151], v[180:183], v[84:87]
	v_mfma_f32_16x16x32_bf16 v[80:83], v[156:159], v[180:183], v[80:83]
	v_mfma_f32_16x16x32_bf16 v[68:71], v[148:151], v[204:207], v[68:71]
	v_mfma_f32_16x16x32_bf16 v[64:67], v[156:159], v[204:207], v[64:67]
	s_setprio 0
	s_barrier
	s_add_i32 s46, s77, s69
	v_lshl_add_u64 v[208:209], s[62:63], 0, v[186:187]
	s_mov_b32 m0, s46
	ds_read_b128 v[160:163], v225 offset:16384
	ds_read_b128 v[164:167], v225 offset:17408
	ds_read_b128 v[168:171], v225 offset:18432
	ds_read_b128 v[172:175], v225 offset:19456
	ds_read_b128 v[176:179], v225 offset:20480
	ds_read_b128 v[180:183], v225 offset:21504
	ds_read_b128 v[200:203], v225 offset:22528
	ds_read_b128 v[204:207], v225 offset:23552
	global_load_lds_dwordx4 v[208:209], off
	s_add_i32 m0, s46, 0x2000
	s_add_u32 s80, s62, 0x40000
	v_lshl_add_u64 v[210:211], s[62:63], 0, v[190:191]
	s_addc_u32 s81, s63, 0
	s_add_i32 s46, s78, s69
	global_load_lds_dwordx4 v[210:211], off
	v_lshl_add_u64 v[212:213], s[80:81], 0, v[186:187]
	s_mov_b32 m0, s46
	v_lshl_add_u64 v[214:215], s[64:65], 0, v[188:189]
	global_load_lds_dwordx4 v[212:213], off
	v_lshl_add_u64 v[212:213], s[80:81], 0, v[190:191]
	s_add_i32 m0, s46, 0x2000
	s_nop 0
	global_load_lds_dwordx4 v[212:213], off
	v_lshl_add_u64 v[212:213], s[64:65], 0, v[184:185]
	s_mov_b32 m0, s70
	s_nop 0
	global_load_lds_dwordx4 v[212:213], off
	s_mov_b32 m0, s71
	s_nop 0
	global_load_lds_dwordx4 v[214:215], off
	s_cmp_lg_u32 s59, -2
	s_cbranch_scc1 .Lzacc5b
	v_pk_mov_b32 v[0:1], 0, 0
	v_pk_mov_b32 v[2:3], 0, 0
	v_pk_mov_b32 v[4:5], 0, 0
	v_pk_mov_b32 v[6:7], 0, 0
	v_pk_mov_b32 v[8:9], 0, 0
	v_pk_mov_b32 v[10:11], 0, 0
	v_pk_mov_b32 v[12:13], 0, 0
	v_pk_mov_b32 v[14:15], 0, 0
	v_pk_mov_b32 v[16:17], 0, 0
	v_pk_mov_b32 v[18:19], 0, 0
	v_pk_mov_b32 v[20:21], 0, 0
	v_pk_mov_b32 v[22:23], 0, 0
	v_pk_mov_b32 v[24:25], 0, 0
	v_pk_mov_b32 v[26:27], 0, 0
	v_pk_mov_b32 v[28:29], 0, 0
	v_pk_mov_b32 v[30:31], 0, 0
	v_pk_mov_b32 v[32:33], 0, 0
	v_pk_mov_b32 v[34:35], 0, 0
	v_pk_mov_b32 v[36:37], 0, 0
	v_pk_mov_b32 v[38:39], 0, 0
	v_pk_mov_b32 v[40:41], 0, 0
	v_pk_mov_b32 v[42:43], 0, 0
	v_pk_mov_b32 v[44:45], 0, 0
	v_pk_mov_b32 v[46:47], 0, 0
	v_pk_mov_b32 v[48:49], 0, 0
	v_pk_mov_b32 v[50:51], 0, 0
	v_pk_mov_b32 v[52:53], 0, 0
	v_pk_mov_b32 v[54:55], 0, 0
	v_pk_mov_b32 v[56:57], 0, 0
	v_pk_mov_b32 v[58:59], 0, 0
	v_pk_mov_b32 v[60:61], 0, 0
	v_pk_mov_b32 v[62:63], 0, 0

.LBB0_991:
	ds_read_b128 v[128:131], v204
	ds_read_b128 v[132:135], v204 offset:1024
	ds_read_b128 v[136:139], v204 offset:2048
	ds_read_b128 v[140:143], v204 offset:3072
	ds_read_b128 v[144:147], v205
	ds_read_b128 v[148:151], v205 offset:1024
	ds_read_b128 v[152:155], v205 offset:2048
	ds_read_b128 v[156:159], v205 offset:3072
	s_add_u32 s10, s8, 0xfffc0080
	s_addc_u32 s11, s9, -1
	s_cmp_eq_u32 s60, 12
	s_cselect_b32 s15, s4, s11
	s_cselect_b32 s14, s5, s10
	s_cselect_b32 s11, s12, s55
	s_cselect_b32 s10, s39, s51
	v_lshl_add_u64 v[214:215], s[8:9], 0, v[178:179]
	s_add_i32 m0, s53, 0xc000
	ds_read_b128 v[160:163], v206
	ds_read_b128 v[164:167], v206 offset:1024
	ds_read_b128 v[186:189], v206 offset:2048
	ds_read_b128 v[190:193], v206 offset:3072
	ds_read_b128 v[194:197], v206 offset:4096
	ds_read_b128 v[198:201], v206 offset:5120
	ds_read_b128 v[210:213], v206 offset:6144
	ds_read_b128 v[218:221], v206 offset:7168
	global_load_lds_dwordx4 v[214:215], off
	v_lshl_add_u64 v[214:215], s[8:9], 0, v[180:181]
	s_add_i32 m0, s53, 0xe000
	s_nop 0
	global_load_lds_dwordx4 v[214:215], off
	s_cmp_lg_u32 s60, -2
	s_cbranch_scc1 .Lzacc6a
	v_pk_mov_b32 v[24:25], 0, 0
	v_pk_mov_b32 v[26:27], 0, 0
	v_pk_mov_b32 v[36:37], 0, 0
	v_pk_mov_b32 v[38:39], 0, 0
	v_pk_mov_b32 v[52:53], 0, 0
	v_pk_mov_b32 v[54:55], 0, 0
	v_pk_mov_b32 v[64:65], 0, 0
	v_pk_mov_b32 v[66:67], 0, 0
	v_pk_mov_b32 v[80:81], 0, 0
	v_pk_mov_b32 v[82:83], 0, 0
	v_pk_mov_b32 v[84:85], 0, 0
	v_pk_mov_b32 v[86:87], 0, 0
	v_pk_mov_b32 v[88:89], 0, 0
	v_pk_mov_b32 v[90:91], 0, 0
	v_pk_mov_b32 v[92:93], 0, 0
	v_pk_mov_b32 v[94:95], 0, 0
	v_pk_mov_b32 v[96:97], 0, 0
	v_pk_mov_b32 v[98:99], 0, 0
	v_pk_mov_b32 v[100:101], 0, 0
	v_pk_mov_b32 v[102:103], 0, 0
	v_pk_mov_b32 v[104:105], 0, 0
	v_pk_mov_b32 v[106:107], 0, 0
	v_pk_mov_b32 v[108:109], 0, 0
	v_pk_mov_b32 v[110:111], 0, 0
	v_pk_mov_b32 v[112:113], 0, 0
	v_pk_mov_b32 v[114:115], 0, 0
	v_pk_mov_b32 v[116:117], 0, 0
	v_pk_mov_b32 v[118:119], 0, 0
	v_pk_mov_b32 v[120:121], 0, 0
	v_pk_mov_b32 v[122:123], 0, 0
	v_pk_mov_b32 v[124:125], 0, 0
	v_pk_mov_b32 v[126:127], 0, 0
.Lzacc6a:
	s_waitcnt vmcnt(8)
	s_waitcnt lgkmcnt(0)
	s_barrier
	s_setprio 1
	s_waitcnt lgkmcnt(0)
	v_mfma_f32_16x16x32_bf16 v[124:127], v[128:131], v[160:163], v[124:127]
	v_mfma_f32_16x16x32_bf16 v[120:123], v[136:139], v[160:163], v[120:123]
	v_mfma_f32_16x16x32_bf16 v[116:119], v[128:131], v[186:189], v[116:119]
	v_mfma_f32_16x16x32_bf16 v[112:115], v[136:139], v[186:189], v[112:115]
	v_mfma_f32_16x16x32_bf16 v[108:111], v[128:131], v[194:197], v[108:111]
	v_mfma_f32_16x16x32_bf16 v[104:107], v[136:139], v[194:197], v[104:107]
	v_mfma_f32_16x16x32_bf16 v[92:95], v[128:131], v[210:213], v[92:95]
	v_mfma_f32_16x16x32_bf16 v[84:87], v[136:139], v[210:213], v[84:87]
	v_mfma_f32_16x16x32_bf16 v[124:127], v[132:135], v[164:167], v[124:127]
	v_mfma_f32_16x16x32_bf16 v[120:123], v[140:143], v[164:167], v[120:123]
	v_mfma_f32_16x16x32_bf16 v[116:119], v[132:135], v[190:193], v[116:119]
	v_mfma_f32_16x16x32_bf16 v[112:115], v[140:143], v[190:193], v[112:115]
	v_mfma_f32_16x16x32_bf16 v[108:111], v[132:135], v[198:201], v[108:111]
	v_mfma_f32_16x16x32_bf16 v[104:107], v[140:143], v[198:201], v[104:107]
	v_mfma_f32_16x16x32_bf16 v[92:95], v[132:135], v[218:221], v[92:95]
	v_mfma_f32_16x16x32_bf16 v[84:87], v[140:143], v[218:221], v[84:87]
	s_setprio 0
	s_setprio 1
	v_mfma_f32_16x16x32_bf16 v[88:91], v[144:147], v[160:163], v[88:91]
	v_mfma_f32_16x16x32_bf16 v[24:27], v[152:155], v[160:163], v[24:27]
	v_mfma_f32_16x16x32_bf16 v[100:103], v[144:147], v[186:189], v[100:103]
	v_mfma_f32_16x16x32_bf16 v[36:39], v[152:155], v[186:189], v[36:39]
	v_mfma_f32_16x16x32_bf16 v[96:99], v[144:147], v[194:197], v[96:99]
	v_mfma_f32_16x16x32_bf16 v[52:55], v[152:155], v[194:197], v[52:55]
	v_mfma_f32_16x16x32_bf16 v[80:83], v[144:147], v[210:213], v[80:83]
	v_mfma_f32_16x16x32_bf16 v[64:67], v[152:155], v[210:213], v[64:67]
	v_mfma_f32_16x16x32_bf16 v[88:91], v[148:151], v[164:167], v[88:91]
	v_mfma_f32_16x16x32_bf16 v[24:27], v[156:159], v[164:167], v[24:27]
	v_mfma_f32_16x16x32_bf16 v[100:103], v[148:151], v[190:193], v[100:103]
	v_mfma_f32_16x16x32_bf16 v[36:39], v[156:159], v[190:193], v[36:39]
	v_mfma_f32_16x16x32_bf16 v[96:99], v[148:151], v[198:201], v[96:99]
	v_mfma_f32_16x16x32_bf16 v[52:55], v[156:159], v[198:201], v[52:55]
	v_mfma_f32_16x16x32_bf16 v[80:83], v[148:151], v[218:221], v[80:83]
	v_mfma_f32_16x16x32_bf16 v[64:67], v[156:159], v[218:221], v[64:67]
	s_setprio 0
	s_barrier
	s_add_i32 s46, s82, s66
	v_lshl_add_u64 v[214:215], s[10:11], 0, v[172:173]
	s_mov_b32 m0, s46
	ds_read_b128 v[160:163], v206 offset:16384
	ds_read_b128 v[164:167], v206 offset:17408
	ds_read_b128 v[186:189], v206 offset:18432
	ds_read_b128 v[190:193], v206 offset:19456
	ds_read_b128 v[194:197], v206 offset:20480
	ds_read_b128 v[198:201], v206 offset:21504
	ds_read_b128 v[210:213], v206 offset:22528
	ds_read_b128 v[218:221], v206 offset:23552
	global_load_lds_dwordx4 v[214:215], off
	s_add_i32 m0, s46, 0x2000
	s_add_u32 s92, s10, 0x40000
	v_lshl_add_u64 v[222:223], s[10:11], 0, v[168:169]
	s_addc_u32 s93, s11, 0
	s_add_i32 s46, s83, s66
	global_load_lds_dwordx4 v[222:223], off
	v_lshl_add_u64 v[224:225], s[92:93], 0, v[172:173]
	s_mov_b32 m0, s46
	v_lshl_add_u64 v[226:227], s[14:15], 0, v[170:171]
	global_load_lds_dwordx4 v[224:225], off
	v_lshl_add_u64 v[224:225], s[92:93], 0, v[168:169]
	s_add_i32 m0, s46, 0x2000
	s_nop 0
	global_load_lds_dwordx4 v[224:225], off
	v_lshl_add_u64 v[224:225], s[14:15], 0, v[174:175]
	s_mov_b32 m0, s53
	s_nop 0
	global_load_lds_dwordx4 v[224:225], off
	s_mov_b32 m0, s67
	s_nop 0
	global_load_lds_dwordx4 v[226:227], off
	s_cmp_lg_u32 s60, -2
	s_cbranch_scc1 .Lzacc6b
	v_pk_mov_b32 v[0:1], 0, 0
	v_pk_mov_b32 v[2:3], 0, 0
	v_pk_mov_b32 v[4:5], 0, 0
	v_pk_mov_b32 v[6:7], 0, 0
	v_pk_mov_b32 v[8:9], 0, 0
	v_pk_mov_b32 v[10:11], 0, 0
	v_pk_mov_b32 v[12:13], 0, 0
	v_pk_mov_b32 v[14:15], 0, 0
	v_pk_mov_b32 v[16:17], 0, 0
	v_pk_mov_b32 v[18:19], 0, 0
	v_pk_mov_b32 v[20:21], 0, 0
	v_pk_mov_b32 v[22:23], 0, 0
	v_pk_mov_b32 v[28:29], 0, 0
	v_pk_mov_b32 v[30:31], 0, 0
	v_pk_mov_b32 v[32:33], 0, 0
	v_pk_mov_b32 v[34:35], 0, 0
	v_pk_mov_b32 v[40:41], 0, 0
	v_pk_mov_b32 v[42:43], 0, 0
	v_pk_mov_b32 v[44:45], 0, 0
	v_pk_mov_b32 v[46:47], 0, 0
	v_pk_mov_b32 v[48:49], 0, 0
	v_pk_mov_b32 v[50:51], 0, 0
	v_pk_mov_b32 v[56:57], 0, 0
	v_pk_mov_b32 v[58:59], 0, 0
	v_pk_mov_b32 v[60:61], 0, 0
	v_pk_mov_b32 v[62:63], 0, 0
	v_pk_mov_b32 v[68:69], 0, 0
	v_pk_mov_b32 v[70:71], 0, 0
	v_pk_mov_b32 v[72:73], 0, 0
	v_pk_mov_b32 v[74:75], 0, 0
	v_pk_mov_b32 v[76:77], 0, 0
	v_pk_mov_b32 v[78:79], 0, 0

.LBB0_1151:
	ds_read_b128 v[112:115], v223
	ds_read_b128 v[124:127], v223 offset:1024
	ds_read_b128 v[136:139], v223 offset:2048
	ds_read_b128 v[140:143], v223 offset:3072
	ds_read_b128 v[144:147], v224
	ds_read_b128 v[148:151], v224 offset:1024
	ds_read_b128 v[152:155], v224 offset:2048
	ds_read_b128 v[156:159], v224 offset:3072
	s_add_u32 s38, s36, 0x100
	s_addc_u32 s39, s37, 0
	s_cmp_eq_u32 s71, 40
	s_cselect_b32 s49, s11, s39
	s_cselect_b32 s48, s10, s38
	s_cselect_b32 s47, s35, s70
	s_cselect_b32 s46, s34, s69
	v_lshl_add_u64 v[208:209], s[36:37], 0, v[192:193]
	s_add_i32 m0, s55, 0xc000
	ds_read_b128 v[160:163], v225
	ds_read_b128 v[164:167], v225 offset:1024
	ds_read_b128 v[168:171], v225 offset:2048
	ds_read_b128 v[172:175], v225 offset:3072
	ds_read_b128 v[176:179], v225 offset:4096
	ds_read_b128 v[180:183], v225 offset:5120
	ds_read_b128 v[200:203], v225 offset:6144
	ds_read_b128 v[204:207], v225 offset:7168
	global_load_lds_dwordx4 v[208:209], off
	v_lshl_add_u64 v[208:209], s[36:37], 0, v[194:195]
	s_add_i32 m0, s55, 0xe000
	s_nop 0
	global_load_lds_dwordx4 v[208:209], off
	s_cmp_lg_u32 s71, -2
	s_cbranch_scc1 .Lzacc7a
	v_pk_mov_b32 v[64:65], 0, 0
	v_pk_mov_b32 v[66:67], 0, 0
	v_pk_mov_b32 v[68:69], 0, 0
	v_pk_mov_b32 v[70:71], 0, 0
	v_pk_mov_b32 v[72:73], 0, 0
	v_pk_mov_b32 v[74:75], 0, 0
	v_pk_mov_b32 v[76:77], 0, 0
	v_pk_mov_b32 v[78:79], 0, 0
	v_pk_mov_b32 v[80:81], 0, 0
	v_pk_mov_b32 v[82:83], 0, 0
	v_pk_mov_b32 v[84:85], 0, 0
	v_pk_mov_b32 v[86:87], 0, 0
	v_pk_mov_b32 v[88:89], 0, 0
	v_pk_mov_b32 v[90:91], 0, 0
	v_pk_mov_b32 v[92:93], 0, 0
	v_pk_mov_b32 v[94:95], 0, 0
	v_pk_mov_b32 v[96:97], 0, 0
	v_pk_mov_b32 v[98:99], 0, 0
	v_pk_mov_b32 v[100:101], 0, 0
	v_pk_mov_b32 v[102:103], 0, 0
	v_pk_mov_b32 v[104:105], 0, 0
	v_pk_mov_b32 v[106:107], 0, 0
	v_pk_mov_b32 v[108:109], 0, 0
	v_pk_mov_b32 v[110:111], 0, 0
	v_pk_mov_b32 v[116:117], 0, 0
	v_pk_mov_b32 v[118:119], 0, 0
	v_pk_mov_b32 v[120:121], 0, 0
	v_pk_mov_b32 v[122:123], 0, 0
	v_pk_mov_b32 v[128:129], 0, 0
	v_pk_mov_b32 v[130:131], 0, 0
	v_pk_mov_b32 v[132:133], 0, 0
	v_pk_mov_b32 v[134:135], 0, 0
.Lzacc7a:
	s_waitcnt vmcnt(8)
	s_waitcnt lgkmcnt(0)
	s_barrier
	s_setprio 1
	s_waitcnt lgkmcnt(0)
	v_mfma_f32_16x16x32_bf16 v[132:135], v[112:115], v[160:163], v[132:135]
	v_mfma_f32_16x16x32_bf16 v[128:131], v[136:139], v[160:163], v[128:131]
	v_mfma_f32_16x16x32_bf16 v[108:111], v[112:115], v[168:171], v[108:111]
	v_mfma_f32_16x16x32_bf16 v[104:107], v[136:139], v[168:171], v[104:107]
	v_mfma_f32_16x16x32_bf16 v[92:95], v[112:115], v[176:179], v[92:95]
	v_mfma_f32_16x16x32_bf16 v[88:91], v[136:139], v[176:179], v[88:91]
	v_mfma_f32_16x16x32_bf16 v[76:79], v[112:115], v[200:203], v[76:79]
	v_mfma_f32_16x16x32_bf16 v[72:75], v[136:139], v[200:203], v[72:75]
	v_mfma_f32_16x16x32_bf16 v[132:135], v[124:127], v[164:167], v[132:135]
	v_mfma_f32_16x16x32_bf16 v[128:131], v[140:143], v[164:167], v[128:131]
	v_mfma_f32_16x16x32_bf16 v[108:111], v[124:127], v[172:175], v[108:111]
	v_mfma_f32_16x16x32_bf16 v[104:107], v[140:143], v[172:175], v[104:107]
	v_mfma_f32_16x16x32_bf16 v[92:95], v[124:127], v[180:183], v[92:95]
	v_mfma_f32_16x16x32_bf16 v[88:91], v[140:143], v[180:183], v[88:91]
	v_mfma_f32_16x16x32_bf16 v[76:79], v[124:127], v[204:207], v[76:79]
	v_mfma_f32_16x16x32_bf16 v[72:75], v[140:143], v[204:207], v[72:75]
	s_setprio 0
	s_setprio 1
	v_mfma_f32_16x16x32_bf16 v[120:123], v[144:147], v[160:163], v[120:123]
	v_mfma_f32_16x16x32_bf16 v[116:119], v[152:155], v[160:163], v[116:119]
	v_mfma_f32_16x16x32_bf16 v[100:103], v[144:147], v[168:171], v[100:103]
	v_mfma_f32_16x16x32_bf16 v[96:99], v[152:155], v[168:171], v[96:99]
	v_mfma_f32_16x16x32_bf16 v[84:87], v[144:147], v[176:179], v[84:87]
	v_mfma_f32_16x16x32_bf16 v[80:83], v[152:155], v[176:179], v[80:83]
	v_mfma_f32_16x16x32_bf16 v[68:71], v[144:147], v[200:203], v[68:71]
	v_mfma_f32_16x16x32_bf16 v[64:67], v[152:155], v[200:203], v[64:67]
	v_mfma_f32_16x16x32_bf16 v[120:123], v[148:151], v[164:167], v[120:123]
	v_mfma_f32_16x16x32_bf16 v[116:119], v[156:159], v[164:167], v[116:119]
	v_mfma_f32_16x16x32_bf16 v[100:103], v[148:151], v[172:175], v[100:103]
	v_mfma_f32_16x16x32_bf16 v[96:99], v[156:159], v[172:175], v[96:99]
	v_mfma_f32_16x16x32_bf16 v[84:87], v[148:151], v[180:183], v[84:87]
	v_mfma_f32_16x16x32_bf16 v[80:83], v[156:159], v[180:183], v[80:83]
	v_mfma_f32_16x16x32_bf16 v[68:71], v[148:151], v[204:207], v[68:71]
	v_mfma_f32_16x16x32_bf16 v[64:67], v[156:159], v[204:207], v[64:67]
	s_setprio 0
	s_barrier
	s_add_i32 s36, s63, s54
	v_lshl_add_u64 v[208:209], s[46:47], 0, v[186:187]
	s_mov_b32 m0, s36
	ds_read_b128 v[160:163], v225 offset:16384
	ds_read_b128 v[164:167], v225 offset:17408
	ds_read_b128 v[168:171], v225 offset:18432
	ds_read_b128 v[172:175], v225 offset:19456
	ds_read_b128 v[176:179], v225 offset:20480
	ds_read_b128 v[180:183], v225 offset:21504
	ds_read_b128 v[200:203], v225 offset:22528
	ds_read_b128 v[204:207], v225 offset:23552
	global_load_lds_dwordx4 v[208:209], off
	s_add_i32 m0, s36, 0x2000
	s_add_u32 s36, s46, 0xb0000
	v_lshl_add_u64 v[210:211], s[46:47], 0, v[190:191]
	s_addc_u32 s37, s47, 0
	s_add_i32 s72, s64, s54
	global_load_lds_dwordx4 v[210:211], off
	v_lshl_add_u64 v[212:213], s[36:37], 0, v[186:187]
	s_mov_b32 m0, s72
	v_lshl_add_u64 v[214:215], s[48:49], 0, v[188:189]
	global_load_lds_dwordx4 v[212:213], off
	v_lshl_add_u64 v[212:213], s[36:37], 0, v[190:191]
	s_add_i32 m0, s72, 0x2000
	s_nop 0
	global_load_lds_dwordx4 v[212:213], off
	v_lshl_add_u64 v[212:213], s[48:49], 0, v[184:185]
	s_mov_b32 m0, s55
	s_nop 0
	global_load_lds_dwordx4 v[212:213], off
	s_mov_b32 m0, s56
	s_nop 0
	global_load_lds_dwordx4 v[214:215], off
	s_cmp_lg_u32 s71, -2
	s_cbranch_scc1 .Lzacc7b
	v_pk_mov_b32 v[0:1], 0, 0
	v_pk_mov_b32 v[2:3], 0, 0
	v_pk_mov_b32 v[4:5], 0, 0
	v_pk_mov_b32 v[6:7], 0, 0
	v_pk_mov_b32 v[8:9], 0, 0
	v_pk_mov_b32 v[10:11], 0, 0
	v_pk_mov_b32 v[12:13], 0, 0
	v_pk_mov_b32 v[14:15], 0, 0
	v_pk_mov_b32 v[16:17], 0, 0
	v_pk_mov_b32 v[18:19], 0, 0
	v_pk_mov_b32 v[20:21], 0, 0
	v_pk_mov_b32 v[22:23], 0, 0
	v_pk_mov_b32 v[24:25], 0, 0
	v_pk_mov_b32 v[26:27], 0, 0
	v_pk_mov_b32 v[28:29], 0, 0
	v_pk_mov_b32 v[30:31], 0, 0
	v_pk_mov_b32 v[32:33], 0, 0
	v_pk_mov_b32 v[34:35], 0, 0
	v_pk_mov_b32 v[36:37], 0, 0
	v_pk_mov_b32 v[38:39], 0, 0
	v_pk_mov_b32 v[40:41], 0, 0
	v_pk_mov_b32 v[42:43], 0, 0
	v_pk_mov_b32 v[44:45], 0, 0
	v_pk_mov_b32 v[46:47], 0, 0
	v_pk_mov_b32 v[48:49], 0, 0
	v_pk_mov_b32 v[50:51], 0, 0
	v_pk_mov_b32 v[52:53], 0, 0
	v_pk_mov_b32 v[54:55], 0, 0
	v_pk_mov_b32 v[56:57], 0, 0
	v_pk_mov_b32 v[58:59], 0, 0
	v_pk_mov_b32 v[60:61], 0, 0
	v_pk_mov_b32 v[62:63], 0, 0
